# mixer-A near part, peeled first iteration: 16 serialized bias-table ds_read2 (own address add + wait each) batched into one burst from two base registers
# speedup vs baseline: 1.0037x; 1.0037x over previous
; template <int MODE, int NQ, int TS, bool FAST = false> ...
;     ...
;   const int kkey_ = wave * 8 + (lane >> 3);
;   const bf16_t* kg = proj + (size_t)(seq_base + TS * kkey_) * ld + koff + (((lane & 7) ^ ((kkey_ >> 1) & 7)) * 8);
;   const bf16_t* vg = proj + (size_t)(seq_base + TS * ((wave & 3) * 16 + (lane >> 2))) * ld + voff + ((wave >> 2) * 4 + (lane & 3)) * 8;
;   const unsigned sdst = (unsigned)__builtin_amdgcn_readfirstlane(wave * 1024);
;     ...
;   const int ktl = kt1 - 1;
;   constexpr int TAB_OFF = 6 * 16384, TAB_N = (MODE == 3) ? 640 : 1024, TAB_ZERO = TAB_N / 2;
;   if (MODE == 0 || MODE == 3) {
;     float* tab = (float*)(lds + TAB_OFF);
;     for (int e = tid; e < TAB_N; e += 512) {
;       const int oo = e - TAB_ZERO, aa = oo < 0 ? -oo : oo;
;       if (MODE == 0) {
;         const int c = (aa <= 64 ? 1 : 0) + (((oo & 3) == 0 && aa <= 256) ? 1 : 0) + (((oo & 15) == 0 && aa <= 256) ? 1 : 0);
;         tab[e] = c ? (-slope2 * (float)aa + (c == 1 ? 0.f : (c == 2 ? 1.f : 1.5849625007f))) : -1e30f;
;       } else {
;         tab[e] = (aa >= 17 && aa <= 64) ? -slope2 * (float)(16 * aa) : -1e30f;
;       }
;     }
;   }
;   if (MODE == 2) {
;     float* tab = (float*)(lds + TAB_OFF) + (wave & 3) * 512;
; #pragma unroll
;     for (int i = 0; i < 4; ++i) { const int e = (wave >> 2) * 64 + lane + 128 * i; const int oo = e - 256, aa = oo < 0 ? -oo : oo; tab[e] = (aa <= 128) ? -slope2 * (float)aa : -1e30f; }
;   }
;   ATT_ISSUE(kt0, 0); ATT_ISSUE((kt0 + 1 < ktl ? kt0 + 1 : ktl), 1); ATT_ISSUE((kt0 + 2 < ktl ? kt0 + 2 : ktl), 2); ATT_ISSUE((kt0 + 3 < ktl ? kt0 + 3 : ktl), 3);
;   asm volatile("s_waitcnt vmcnt(6) lgkmcnt(0)\n\ts_barrier" ::: "memory");
;   int kfo4[4];
; #pragma unroll
;   for (int ks = 0; ks < 4; ++ks) kfo4[ks] = r32 * 128 + (((2 * ks + hh) ^ ((r32 >> 1) & 7)) << 4);
;   const int vfo = 8192 + (4 * hh + ((lane & 15) >> 2)) * 64 + ((lane >> 4) & 1) * 32 + (lane & 3) * 8;
;   const bool g2 = wave >= 4;
;     ...
;   for (int kt = kt0; kt < kt1; ++kt) {
;     { const int tn = (kt + 4 < ktl) ? kt + 4 : ktl; int s4 = slot + 4; if (s4 >= NS) s4 -= NS; ATT_ISSUE(tn, s4); }
;     const bool act = tile_active(kt);
;     if (!g2) {
;       if (act) { QK(slot); SM(kt); PV(slot); }
;     } else {
;       if (kt > kt0 && tile_active(kt - 1)) PV(sp);
;       if (act) { QK(slot); SM(kt); }
.LBB0_377:
	s_or_b64 exec, exec, s[28:29]
	s_and_b64 s[0:1], s[26:27], exec
	s_cselect_b32 s0, 0x100, 64
	s_add_i32 s1, s7, 0x1ff
	v_lshrrev_b32_e32 v0, 3, v40
	s_ashr_i32 s1, s1, 6
	v_lshl_or_b32 v0, v38, 3, v0
	s_add_i32 s5, s1, 1
	v_add_u32_e32 v35, s6, v0
	v_lshrrev_b32_e32 v0, 1, v0
	s_cmp_lt_i32 s1, s0
	v_mov_b64_e32 v[42:43], s[66:67]
	v_xor_b32_e32 v0, v0, v34
	s_cselect_b32 s5, s5, s0
	v_mad_i64_i32 v[42:43], s[0:1], v35, s22, v[42:43]
	v_lshlrev_b32_e32 v0, 4, v0
	v_lshl_add_u64 v[42:43], v[42:43], 0, s[76:77]
	v_and_b32_e32 v0, 0x70, v0
	v_lshl_add_u64 v[84:85], v[42:43], 0, v[0:1]
	v_lshlrev_b32_e32 v0, 4, v38
	v_and_b32_e32 v0, 48, v0
	v_lshrrev_b32_e32 v35, 2, v40
	v_or3_b32 v0, v35, v0, s6
	v_mul_u32_u24_e32 v0, 0x900, v0
	v_lshlrev_b32_e32 v0, 1, v0
	s_mov_b32 s0, 0x1ffffffc
	v_lshl_add_u64 v[40:41], s[66:67], 0, v[0:1]
	v_and_or_b32 v0, v38, s0, v39
	s_addk_i32 s7, 0xff00
	v_lshlrev_b32_e32 v42, 3, v0
	s_ashr_i32 s16, s7, 6
	v_lshl_add_u64 v[40:41], v[40:41], 0, s[76:77]
	v_ashrrev_i32_e32 v43, 31, v42
	s_max_i32 s7, s16, 0
	v_lshl_add_u64 v[86:87], v[42:43], 1, v[40:41]
	s_lshl_b32 s15, s8, 10
	v_mad_u64_u32 v[40:41], s[0:1], s7, v237, v[84:85]
	s_mov_b64 s[26:27], 0x400
	v_lshl_add_u64 v[40:41], v[40:41], 0, s[26:27]
	s_mov_b32 m0, s15
	s_add_i32 s14, s5, -1
	global_load_lds_dwordx4 v[40:41], off
	v_mad_u64_u32 v[40:41], s[0:1], s7, v237, v[86:87]
	s_mov_b64 s[18:19], 0x800
	s_or_b32 s8, s7, 1
	v_lshl_add_u64 v[40:41], v[40:41], 0, s[18:19]
	s_add_i32 m0, s15, 0x2000
	s_min_i32 s12, s8, s14
	global_load_lds_dwordx4 v[40:41], off
	v_mad_i64_i32 v[40:41], s[0:1], s12, v237, v[84:85]
	v_lshl_add_u64 v[40:41], v[40:41], 0, s[26:27]
	s_add_i32 m0, s15, 0x4000
	v_lshlrev_b32_e32 v0, 4, v34
	global_load_lds_dwordx4 v[40:41], off
	v_mad_i64_i32 v[40:41], s[0:1], s12, v237, v[86:87]
	s_or_b32 s0, s7, 2
	v_lshl_add_u64 v[40:41], v[40:41], 0, s[18:19]
	s_add_i32 m0, s15, 0x6000
	s_min_i32 s12, s0, s14
	global_load_lds_dwordx4 v[40:41], off
	v_mad_i64_i32 v[40:41], s[0:1], s12, v237, v[84:85]
	v_lshl_add_u64 v[40:41], v[40:41], 0, s[26:27]
	s_add_i32 m0, s15, 0x8000
	v_and_b32_e32 v0, 0xc0, v0
	global_load_lds_dwordx4 v[40:41], off
	v_mad_i64_i32 v[40:41], s[0:1], s12, v237, v[86:87]
	s_or_b32 s0, s7, 3
	v_lshl_add_u64 v[40:41], v[40:41], 0, s[18:19]
	s_add_i32 m0, s15, 0xa000
	s_min_i32 s12, s0, s14
	global_load_lds_dwordx4 v[40:41], off
	v_mad_i64_i32 v[40:41], s[0:1], s12, v237, v[84:85]
	v_lshl_add_u64 v[40:41], v[40:41], 0, s[26:27]
	s_add_i32 m0, s15, 0xc000
	v_lshlrev_b32_e32 v35, 1, v34
	global_load_lds_dwordx4 v[40:41], off
	v_mad_i64_i32 v[40:41], s[0:1], s12, v237, v[86:87]
	v_lshl_add_u64 v[40:41], v[40:41], 0, s[18:19]
	s_add_i32 m0, s15, 0xe000
	v_lshl_or_b32 v0, v37, 8, v0
	global_load_lds_dwordx4 v[40:41], off
	s_waitcnt vmcnt(6) lgkmcnt(0)
	s_barrier
	v_and_b32_e32 v35, 32, v35
	v_lshlrev_b32_e32 v39, 3, v39
	v_lshlrev_b32_e32 v95, 2, v37
	v_lshlrev_b32_e32 v18, 16, v2
	v_and_b32_e32 v19, 0xffff0000, v2
	v_lshlrev_b32_e32 v20, 16, v3
	v_and_b32_e32 v21, 0xffff0000, v3
	v_lshlrev_b32_e32 v2, 16, v4
	v_and_b32_e32 v3, 0xffff0000, v4
	v_lshlrev_b32_e32 v4, 16, v5
	v_and_b32_e32 v5, 0xffff0000, v5
	v_lshlrev_b32_e32 v22, 16, v6
	v_and_b32_e32 v23, 0xffff0000, v6
	v_lshlrev_b32_e32 v24, 16, v7
	v_and_b32_e32 v25, 0xffff0000, v7
	v_lshlrev_b32_e32 v6, 16, v8
	v_and_b32_e32 v7, 0xffff0000, v8
	v_lshlrev_b32_e32 v8, 16, v9
	v_and_b32_e32 v9, 0xffff0000, v9
	v_lshlrev_b32_e32 v26, 16, v10
	v_and_b32_e32 v27, 0xffff0000, v10
	v_lshlrev_b32_e32 v28, 16, v11
	v_and_b32_e32 v29, 0xffff0000, v11
	v_lshlrev_b32_e32 v10, 16, v12
	v_and_b32_e32 v11, 0xffff0000, v12
	v_lshlrev_b32_e32 v12, 16, v13
	v_and_b32_e32 v13, 0xffff0000, v13
	v_lshlrev_b32_e32 v30, 16, v14
	v_and_b32_e32 v31, 0xffff0000, v14
	v_lshlrev_b32_e32 v32, 16, v15
	v_and_b32_e32 v33, 0xffff0000, v15
	v_lshlrev_b32_e32 v14, 16, v16
	v_and_b32_e32 v15, 0xffff0000, v16
	v_lshlrev_b32_e32 v16, 16, v17
	v_and_b32_e32 v17, 0xffff0000, v17
	s_mov_b32 s9, 0
	v_or3_b32 v96, v0, v35, v39
	v_cmp_lt_i32_e64 s[38:39], 3, v38
	v_cmp_gt_i32_e64 s[40:41], 4, v38
	s_cmp_lt_i32 s7, s5
	s_cbranch_scc0 .LBB0_410
	s_add_i32 s0, s7, 4
	s_min_u32 s9, s0, s14
	v_mad_u64_u32 v[38:39], s[0:1], s9, v237, v[84:85]
	v_lshl_add_u64 v[38:39], v[38:39], 0, s[26:27]
	s_add_i32 m0, s15, 0x10000
	v_lshrrev_b32_e32 v0, 1, v34
	global_load_lds_dwordx4 v[38:39], off
	v_mad_u64_u32 v[38:39], s[0:1], s9, v237, v[86:87]
	v_lshl_add_u64 v[38:39], v[38:39], 0, s[18:19]
	s_add_i32 m0, s15, 0x12000
	v_bfe_u32 v34, v34, 1, 3
	global_load_lds_dwordx4 v[38:39], off
	s_lshl_b32 s30, s7, 6
	v_bitop3_b32 v35, v37, v34, 6 bitop3:0x36
	v_lshlrev_b32_e32 v38, 7, v103
	v_add_u32_e32 v101, 0xffffff00, v93
	v_add_u32_e32 v102, 0x11f, v93
	s_or_b32 s0, s30, 63
	v_lshl_or_b32 v97, v35, 4, v38
	v_bitop3_b32 v35, v37, v34, 4 bitop3:0x36
	v_bitop3_b32 v34, v37, v34, 2 bitop3:0x36
	v_bitop3_b32 v0, v37, v0, 7 bitop3:0x78
	v_cmp_ge_i32_e32 vcc, s0, v101
	v_cmp_le_i32_e64 s[0:1], s30, v102
	s_mov_b64 s[60:61], 0x400
	s_mov_b64 s[58:59], 0x800
	v_lshl_or_b32 v98, v35, 4, v38
	v_lshl_or_b32 v99, v34, 4, v38
	v_lshl_or_b32 v100, v0, 4, v38
	v_sub_u32_e32 v0, v95, v36
	s_and_b64 s[0:1], vcc, s[0:1]
	s_and_saveexec_b64 s[12:13], s[40:41]
	s_xor_b64 s[26:27], exec, s[12:13]
	s_cbranch_execz .LBB0_384
	s_and_saveexec_b64 s[78:79], s[0:1]
	s_cbranch_execz .LBB0_383
; #define MFMA32(a, b, c) __builtin_amdgcn_mfma_f32_32x32x16_bf16((a), (b), (c), 0, 0, 0)
; template <int MODE, int NQ, int TS, bool FAST = false> ...
;     ...
;   auto QK = [&](int slot) {
;     const char* kb_ = lds + slot * 16384;
; #pragma unroll
;     for (int nq = 0; nq < NQ; ++nq)
; #pragma unroll
;       for (int r = 0; r < 16; ++r) { s[nq][0][r] = 0.f; s[nq][1][r] = 0.f; }
; #pragma unroll
;     for (int ks = 0; ks < 4; ++ks) {
;       const bf16x8 k0 = *(const bf16x8*)(kb_ + kfo4[ks]), k1 = *(const bf16x8*)(kb_ + kfo4[ks] + 4096);
; #pragma unroll
;       for (int nq = 0; nq < NQ; ++nq) { s[nq][0] = MFMA32(k0, qf[nq][ks], s[nq][0]); s[nq][1] = MFMA32(k1, qf[nq][ks], s[nq][1]); }
;     }
;   };
;   auto SM = [&](int kt) {
; #pragma unroll
;     for (int nq = 0; nq < NQ; ++nq) {
;       f32x16& s0 = s[nq][0]; f32x16& s1 = s[nq][1];
;       float mx = -1e30f;
;       if (MODE == 1) {
;       } else if (MODE == 0 || MODE == 3) {
;         const float* tb = (const float*)(lds + TAB_OFF) + (kt * 64 + 4 * hh - (q0w + 32 * nq + r32) + TAB_ZERO);
; #pragma unroll
;         for (int r = 0; r < 16; ++r) {
;           const float va = fmaf(s0[r], C2, tb[(r & 3) + 8 * (r >> 2)]), vb = fmaf(s1[r], C2, tb[(r & 3) + 8 * (r >> 2) + 32]);
;           s0[r] = va; s1[r] = vb; mx = fmaxf(mx, fmaxf(va, vb));
;         }
;       } else {
;         const float* tb = (const float*)(lds + TAB_OFF) + (wave & 3) * 512 + (kt * 64 + 4 * hh - (q0w + 32 * nq + r32) + 256);
; #pragma unroll
;         for (int r = 0; r < 16; ++r) {
;           const float va = fmaf(s0[r], C2, tb[(r & 3) + 8 * (r >> 2)]), vb = fmaf(s1[r], C2, tb[(r & 3) + 8 * (r >> 2) + 32]);
;           s0[r] = va; s1[r] = vb; mx = fmaxf(mx, fmaxf(va, vb));
;         }
;       }
;       float mn;
;       if (MODE == 1) {
;         mn = sink2;
;       } else {
;         if (__any(mx > m2[nq] + 8.f)) {
;           mx = fmaxf(mx, __shfl_xor(mx, 32));
;           mn = fmaxf(m2[nq], mx);
;           const float alpha = __builtin_amdgcn_exp2f(m2[nq] - mn);
;           l[nq] *= alpha;
; #pragma unroll
;           for (int r = 0; r < 16; ++r) { o[nq][0][r] *= alpha; o[nq][1][r] *= alpha; }
;           m2[nq] = mn;
;         }
;         mn = m2[nq];
	ds_read_b128 v[34:37], v100
	ds_read_b128 v[50:53], v100 offset:4096
	ds_read_b128 v[88:91], v99
	ds_read_b128 v[104:107], v99 offset:4096
	v_lshlrev_b32_e32 v0, 2, v0
	s_waitcnt lgkmcnt(0)
	v_mfma_f32_32x32x16_bf16 v[34:49], v[34:37], v[66:69], 0
	v_mfma_f32_32x32x16_bf16 v[50:65], v[50:53], v[66:69], 0
	v_mfma_f32_32x32x16_bf16 v[34:49], v[88:91], v[70:73], v[34:49]
	v_mfma_f32_32x32x16_bf16 v[50:65], v[104:107], v[70:73], v[50:65]
	ds_read_b128 v[88:91], v98
	ds_read_b128 v[104:107], v98 offset:4096
	s_waitcnt lgkmcnt(0)
	v_mfma_f32_32x32x16_bf16 v[34:49], v[88:91], v[74:77], v[34:49]
	v_mfma_f32_32x32x16_bf16 v[50:65], v[104:107], v[74:77], v[50:65]
	ds_read_b128 v[88:91], v97
	ds_read_b128 v[104:107], v97 offset:4096
	s_waitcnt lgkmcnt(0)
	v_mfma_f32_32x32x16_bf16 v[34:49], v[88:91], v[78:81], v[34:49]
	v_mfma_f32_32x32x16_bf16 v[50:65], v[104:107], v[78:81], v[50:65]
	v_lshl_add_u32 v104, s30, 2, v0
	v_add_u32_e32 v140, 0x18800, v104
	v_add_u32_e32 v141, 0x18c00, v104
	ds_read2_b32 v[108:109], v140 offset0:0 offset1:1
	ds_read2_b32 v[110:111], v140 offset0:32 offset1:33
	ds_read2_b32 v[112:113], v140 offset0:2 offset1:3
	ds_read2_b32 v[114:115], v140 offset0:34 offset1:35
	ds_read2_b32 v[116:117], v140 offset0:8 offset1:9
	ds_read2_b32 v[118:119], v140 offset0:40 offset1:41
	ds_read2_b32 v[120:121], v140 offset0:10 offset1:11
	ds_read2_b32 v[122:123], v140 offset0:42 offset1:43
	ds_read2_b32 v[124:125], v140 offset0:16 offset1:17
	ds_read2_b32 v[126:127], v140 offset0:48 offset1:49
	ds_read2_b32 v[128:129], v140 offset0:18 offset1:19
	ds_read2_b32 v[130:131], v140 offset0:50 offset1:51
	ds_read2_b32 v[132:133], v140 offset0:24 offset1:25
	ds_read2_b32 v[134:135], v140 offset0:56 offset1:57
	ds_read2_b32 v[136:137], v140 offset0:26 offset1:27
	ds_read2_b32 v[138:139], v140 offset0:58 offset1:59
	s_waitcnt lgkmcnt(0)
	s_nop 6
	v_fmamk_f32 v0, v34, 0x3e38aa3b, v108
	v_fmamk_f32 v89, v35, 0x3e38aa3b, v109
	s_waitcnt lgkmcnt(0)
	v_fmamk_f32 v88, v50, 0x3e38aa3b, v110
	v_fmamk_f32 v91, v51, 0x3e38aa3b, v111
	v_max_f32_e32 v34, v0, v88
	v_max_f32_e32 v35, v89, v91
	v_max3_f32 v90, v34, s23, v35
	s_waitcnt lgkmcnt(0)
	v_fmamk_f32 v34, v36, 0x3e38aa3b, v112
	v_fmamk_f32 v35, v37, 0x3e38aa3b, v113
	s_waitcnt lgkmcnt(0)
	v_fmamk_f32 v50, v52, 0x3e38aa3b, v114
	v_fmamk_f32 v51, v53, 0x3e38aa3b, v115
	v_max_f32_e32 v36, v34, v50
	v_max_f32_e32 v37, v35, v51
	v_max3_f32 v90, v90, v36, v37
	s_waitcnt lgkmcnt(0)
	v_fmamk_f32 v36, v38, 0x3e38aa3b, v116
	v_fmamk_f32 v37, v39, 0x3e38aa3b, v117
	s_waitcnt lgkmcnt(0)
	v_fmamk_f32 v52, v54, 0x3e38aa3b, v118
	v_fmamk_f32 v53, v55, 0x3e38aa3b, v119
	v_max_f32_e32 v38, v36, v52
	v_max_f32_e32 v39, v37, v53
	v_max3_f32 v90, v90, v38, v39
	s_waitcnt lgkmcnt(0)
	v_fmamk_f32 v38, v40, 0x3e38aa3b, v120
	v_fmamk_f32 v39, v41, 0x3e38aa3b, v121
	s_waitcnt lgkmcnt(0)
	v_fmamk_f32 v54, v56, 0x3e38aa3b, v122
	v_fmamk_f32 v55, v57, 0x3e38aa3b, v123
	v_max_f32_e32 v40, v38, v54
	v_max_f32_e32 v41, v39, v55
	v_max3_f32 v90, v90, v40, v41
	s_waitcnt lgkmcnt(0)
	v_fmamk_f32 v40, v42, 0x3e38aa3b, v124
	v_fmamk_f32 v41, v43, 0x3e38aa3b, v125
	s_waitcnt lgkmcnt(0)
	v_fmamk_f32 v56, v58, 0x3e38aa3b, v126
	v_fmamk_f32 v57, v59, 0x3e38aa3b, v127
	v_max_f32_e32 v42, v40, v56
	v_max_f32_e32 v43, v41, v57
	v_max3_f32 v90, v90, v42, v43
	s_waitcnt lgkmcnt(0)
	v_fmamk_f32 v42, v44, 0x3e38aa3b, v128
	v_fmamk_f32 v43, v45, 0x3e38aa3b, v129
	s_waitcnt lgkmcnt(0)
	v_fmamk_f32 v58, v60, 0x3e38aa3b, v130
	v_fmamk_f32 v59, v61, 0x3e38aa3b, v131
	v_max_f32_e32 v44, v42, v58
	v_max_f32_e32 v45, v43, v59
	v_max3_f32 v90, v90, v44, v45
	s_waitcnt lgkmcnt(0)
	v_fmamk_f32 v44, v46, 0x3e38aa3b, v132
	v_fmamk_f32 v45, v47, 0x3e38aa3b, v133
	s_waitcnt lgkmcnt(0)
	v_fmamk_f32 v60, v62, 0x3e38aa3b, v134
	v_fmamk_f32 v61, v63, 0x3e38aa3b, v135
	v_max_f32_e32 v46, v44, v60
	v_max_f32_e32 v47, v45, v61
	v_max3_f32 v90, v90, v46, v47
	s_waitcnt lgkmcnt(0)
	v_fmamk_f32 v46, v48, 0x3e38aa3b, v136
	v_fmamk_f32 v47, v49, 0x3e38aa3b, v137
	s_waitcnt lgkmcnt(0)
	v_fmamk_f32 v48, v64, 0x3e38aa3b, v138
	v_fmamk_f32 v63, v65, 0x3e38aa3b, v139
	v_max_f32_e32 v62, v46, v48
	v_max_f32_e32 v49, v47, v63
	v_max3_f32 v49, v90, v62, v49
	v_add_f32_e32 v62, 0x41000000, v94
	v_cmp_gt_f32_e32 vcc, v49, v62
	s_cbranch_vccz .LBB0_382
	ds_bpermute_b32 v62, v163, v49
	s_waitcnt lgkmcnt(0)
	v_max3_f32 v49, v94, v49, v62
	v_sub_f32_e32 v62, v94, v49
	v_exp_f32_e32 v62, v62
	v_mov_b32_e32 v94, v49
	v_mul_f32_e32 v92, v92, v62
	v_pk_mul_f32 v[32:33], v[62:63], v[32:33] op_sel_hi:[0,1]
	v_pk_mul_f32 v[30:31], v[62:63], v[30:31] op_sel_hi:[0,1]
	v_pk_mul_f32 v[28:29], v[62:63], v[28:29] op_sel_hi:[0,1]
	v_pk_mul_f32 v[26:27], v[62:63], v[26:27] op_sel_hi:[0,1]
	v_pk_mul_f32 v[24:25], v[62:63], v[24:25] op_sel_hi:[0,1]
	v_pk_mul_f32 v[22:23], v[62:63], v[22:23] op_sel_hi:[0,1]
	v_pk_mul_f32 v[20:21], v[62:63], v[20:21] op_sel_hi:[0,1]
	v_pk_mul_f32 v[18:19], v[62:63], v[18:19] op_sel_hi:[0,1]
	v_pk_mul_f32 v[16:17], v[62:63], v[16:17] op_sel_hi:[0,1]
	v_pk_mul_f32 v[14:15], v[62:63], v[14:15] op_sel_hi:[0,1]
	v_pk_mul_f32 v[12:13], v[62:63], v[12:13] op_sel_hi:[0,1]
	v_pk_mul_f32 v[10:11], v[62:63], v[10:11] op_sel_hi:[0,1]
	v_pk_mul_f32 v[8:9], v[62:63], v[8:9] op_sel_hi:[0,1]
	v_pk_mul_f32 v[6:7], v[62:63], v[6:7] op_sel_hi:[0,1]
	v_pk_mul_f32 v[4:5], v[62:63], v[4:5] op_sel_hi:[0,1]
	v_pk_mul_f32 v[2:3], v[62:63], v[2:3] op_sel_hi:[0,1]

; #define MFMA32(a, b, c) __builtin_amdgcn_mfma_f32_32x32x16_bf16((a), (b), (c), 0, 0, 0)
; template <int MODE, int NQ, int TS, bool FAST = false> ...
;     ...
;   auto QK = [&](int slot) {
;     const char* kb_ = lds + slot * 16384;
; #pragma unroll
;     for (int nq = 0; nq < NQ; ++nq)
; #pragma unroll
;       for (int r = 0; r < 16; ++r) { s[nq][0][r] = 0.f; s[nq][1][r] = 0.f; }
; #pragma unroll
;     for (int ks = 0; ks < 4; ++ks) {
;       const bf16x8 k0 = *(const bf16x8*)(kb_ + kfo4[ks]), k1 = *(const bf16x8*)(kb_ + kfo4[ks] + 4096);
; #pragma unroll
;       for (int nq = 0; nq < NQ; ++nq) { s[nq][0] = MFMA32(k0, qf[nq][ks], s[nq][0]); s[nq][1] = MFMA32(k1, qf[nq][ks], s[nq][1]); }
;     }
;   };
;   auto SM = [&](int kt) {
; #pragma unroll
;     for (int nq = 0; nq < NQ; ++nq) {
;       f32x16& s0 = s[nq][0]; f32x16& s1 = s[nq][1];
;       float mx = -1e30f;
;       if (MODE == 1) {
;       } else if (MODE == 0 || MODE == 3) {
;         const float* tb = (const float*)(lds + TAB_OFF) + (kt * 64 + 4 * hh - (q0w + 32 * nq + r32) + TAB_ZERO);
; #pragma unroll
;         for (int r = 0; r < 16; ++r) {
;           const float va = fmaf(s0[r], C2, tb[(r & 3) + 8 * (r >> 2)]), vb = fmaf(s1[r], C2, tb[(r & 3) + 8 * (r >> 2) + 32]);
;           s0[r] = va; s1[r] = vb; mx = fmaxf(mx, fmaxf(va, vb));
;         }
;       } else {
;         const float* tb = (const float*)(lds + TAB_OFF) + (wave & 3) * 512 + (kt * 64 + 4 * hh - (q0w + 32 * nq + r32) + 256);
; #pragma unroll
;         for (int r = 0; r < 16; ++r) {
;           const float va = fmaf(s0[r], C2, tb[(r & 3) + 8 * (r >> 2)]), vb = fmaf(s1[r], C2, tb[(r & 3) + 8 * (r >> 2) + 32]);
;           s0[r] = va; s1[r] = vb; mx = fmaxf(mx, fmaxf(va, vb));
;         }
;       }
;       float mn;
;       if (MODE == 1) {
;         mn = sink2;
;       } else {
;         if (__any(mx > m2[nq] + 8.f)) {
;           mx = fmaxf(mx, __shfl_xor(mx, 32));
;           mn = fmaxf(m2[nq], mx);
;           const float alpha = __builtin_amdgcn_exp2f(m2[nq] - mn);
;           l[nq] *= alpha;
; #pragma unroll
;           for (int r = 0; r < 16; ++r) { o[nq][0][r] *= alpha; o[nq][1][r] *= alpha; }
;           m2[nq] = mn;
;         }
;         mn = m2[nq];
.LBB0_384:
	s_andn2_saveexec_b64 s[26:27], s[26:27]
	s_cbranch_execz .LBB0_390
	s_and_saveexec_b64 s[28:29], s[0:1]
	s_cbranch_execz .LBB0_389
	ds_read_b128 v[34:37], v100
	ds_read_b128 v[50:53], v100 offset:4096
	ds_read_b128 v[88:91], v99
	ds_read_b128 v[104:107], v99 offset:4096
	v_lshlrev_b32_e32 v0, 2, v0
	s_waitcnt lgkmcnt(0)
	v_mfma_f32_32x32x16_bf16 v[34:49], v[34:37], v[66:69], 0
	v_mfma_f32_32x32x16_bf16 v[50:65], v[50:53], v[66:69], 0
	v_mfma_f32_32x32x16_bf16 v[34:49], v[88:91], v[70:73], v[34:49]
	v_mfma_f32_32x32x16_bf16 v[50:65], v[104:107], v[70:73], v[50:65]
	ds_read_b128 v[88:91], v98
	ds_read_b128 v[104:107], v98 offset:4096
	s_waitcnt lgkmcnt(0)
	v_mfma_f32_32x32x16_bf16 v[34:49], v[88:91], v[74:77], v[34:49]
	v_mfma_f32_32x32x16_bf16 v[50:65], v[104:107], v[74:77], v[50:65]
	ds_read_b128 v[88:91], v97
	ds_read_b128 v[104:107], v97 offset:4096
	s_waitcnt lgkmcnt(0)
	v_mfma_f32_32x32x16_bf16 v[34:49], v[88:91], v[78:81], v[34:49]
	v_mfma_f32_32x32x16_bf16 v[50:65], v[104:107], v[78:81], v[50:65]
	v_lshl_add_u32 v104, s30, 2, v0
	v_add_u32_e32 v140, 0x18800, v104
	v_add_u32_e32 v141, 0x18c00, v104
	ds_read2_b32 v[108:109], v140 offset0:0 offset1:1
	ds_read2_b32 v[110:111], v140 offset0:32 offset1:33
	ds_read2_b32 v[112:113], v140 offset0:2 offset1:3
	ds_read2_b32 v[114:115], v140 offset0:34 offset1:35
	ds_read2_b32 v[116:117], v140 offset0:8 offset1:9
	ds_read2_b32 v[118:119], v140 offset0:40 offset1:41
	ds_read2_b32 v[120:121], v140 offset0:10 offset1:11
	ds_read2_b32 v[122:123], v140 offset0:42 offset1:43
	ds_read2_b32 v[124:125], v140 offset0:16 offset1:17
	ds_read2_b32 v[126:127], v140 offset0:48 offset1:49
	ds_read2_b32 v[128:129], v140 offset0:18 offset1:19
	ds_read2_b32 v[130:131], v140 offset0:50 offset1:51
	ds_read2_b32 v[132:133], v140 offset0:24 offset1:25
	ds_read2_b32 v[134:135], v140 offset0:56 offset1:57
	ds_read2_b32 v[136:137], v140 offset0:26 offset1:27
	ds_read2_b32 v[138:139], v140 offset0:58 offset1:59
	s_waitcnt lgkmcnt(0)
	s_nop 6
	v_fmamk_f32 v0, v34, 0x3e38aa3b, v108
	v_fmamk_f32 v89, v35, 0x3e38aa3b, v109
	s_waitcnt lgkmcnt(0)
	v_fmamk_f32 v88, v50, 0x3e38aa3b, v110
	v_fmamk_f32 v91, v51, 0x3e38aa3b, v111
	v_max_f32_e32 v34, v0, v88
	v_max_f32_e32 v35, v89, v91
	v_max3_f32 v90, v34, s23, v35
	s_waitcnt lgkmcnt(0)
	v_fmamk_f32 v34, v36, 0x3e38aa3b, v112
	v_fmamk_f32 v35, v37, 0x3e38aa3b, v113
	s_waitcnt lgkmcnt(0)
	v_fmamk_f32 v50, v52, 0x3e38aa3b, v114
	v_fmamk_f32 v51, v53, 0x3e38aa3b, v115
	v_max_f32_e32 v36, v34, v50
	v_max_f32_e32 v37, v35, v51
	v_max3_f32 v90, v90, v36, v37
	s_waitcnt lgkmcnt(0)
	v_fmamk_f32 v36, v38, 0x3e38aa3b, v116
	v_fmamk_f32 v37, v39, 0x3e38aa3b, v117
	s_waitcnt lgkmcnt(0)
	v_fmamk_f32 v52, v54, 0x3e38aa3b, v118
	v_fmamk_f32 v53, v55, 0x3e38aa3b, v119
	v_max_f32_e32 v38, v36, v52
	v_max_f32_e32 v39, v37, v53
	v_max3_f32 v90, v90, v38, v39
	s_waitcnt lgkmcnt(0)
	v_fmamk_f32 v38, v40, 0x3e38aa3b, v120
	v_fmamk_f32 v39, v41, 0x3e38aa3b, v121
	s_waitcnt lgkmcnt(0)
	v_fmamk_f32 v54, v56, 0x3e38aa3b, v122
	v_fmamk_f32 v55, v57, 0x3e38aa3b, v123
	v_max_f32_e32 v40, v38, v54
	v_max_f32_e32 v41, v39, v55
	v_max3_f32 v90, v90, v40, v41
	s_waitcnt lgkmcnt(0)
	v_fmamk_f32 v40, v42, 0x3e38aa3b, v124
	v_fmamk_f32 v41, v43, 0x3e38aa3b, v125
	s_waitcnt lgkmcnt(0)
	v_fmamk_f32 v56, v58, 0x3e38aa3b, v126
	v_fmamk_f32 v57, v59, 0x3e38aa3b, v127
	v_max_f32_e32 v42, v40, v56
	v_max_f32_e32 v43, v41, v57
	v_max3_f32 v90, v90, v42, v43
	s_waitcnt lgkmcnt(0)
	v_fmamk_f32 v42, v44, 0x3e38aa3b, v128
	v_fmamk_f32 v43, v45, 0x3e38aa3b, v129
	s_waitcnt lgkmcnt(0)
	v_fmamk_f32 v58, v60, 0x3e38aa3b, v130
	v_fmamk_f32 v59, v61, 0x3e38aa3b, v131
	v_max_f32_e32 v44, v42, v58
	v_max_f32_e32 v45, v43, v59
	v_max3_f32 v90, v90, v44, v45
	s_waitcnt lgkmcnt(0)
	v_fmamk_f32 v44, v46, 0x3e38aa3b, v132
	v_fmamk_f32 v45, v47, 0x3e38aa3b, v133
	s_waitcnt lgkmcnt(0)
	v_fmamk_f32 v60, v62, 0x3e38aa3b, v134
	v_fmamk_f32 v61, v63, 0x3e38aa3b, v135
	v_max_f32_e32 v46, v44, v60
	v_max_f32_e32 v47, v45, v61
	v_max3_f32 v90, v90, v46, v47
	s_waitcnt lgkmcnt(0)
	v_fmamk_f32 v46, v48, 0x3e38aa3b, v136
	v_fmamk_f32 v47, v49, 0x3e38aa3b, v137
	s_waitcnt lgkmcnt(0)
	v_fmamk_f32 v48, v64, 0x3e38aa3b, v138
	v_fmamk_f32 v63, v65, 0x3e38aa3b, v139
	v_max_f32_e32 v62, v46, v48
	v_max_f32_e32 v49, v47, v63
	v_max3_f32 v49, v90, v62, v49
	v_add_f32_e32 v62, 0x41000000, v94
	v_cmp_gt_f32_e32 vcc, v49, v62
	s_cbranch_vccz .LBB0_388
	ds_bpermute_b32 v62, v163, v49
	s_waitcnt lgkmcnt(0)
	v_max3_f32 v49, v94, v49, v62
	v_sub_f32_e32 v62, v94, v49
	v_exp_f32_e32 v62, v62
	v_mov_b32_e32 v94, v49
	v_mul_f32_e32 v92, v92, v62
	v_pk_mul_f32 v[32:33], v[62:63], v[32:33] op_sel_hi:[0,1]
	v_pk_mul_f32 v[30:31], v[62:63], v[30:31] op_sel_hi:[0,1]
	v_pk_mul_f32 v[28:29], v[62:63], v[28:29] op_sel_hi:[0,1]
	v_pk_mul_f32 v[26:27], v[62:63], v[26:27] op_sel_hi:[0,1]
	v_pk_mul_f32 v[24:25], v[62:63], v[24:25] op_sel_hi:[0,1]
	v_pk_mul_f32 v[22:23], v[62:63], v[22:23] op_sel_hi:[0,1]
	v_pk_mul_f32 v[20:21], v[62:63], v[20:21] op_sel_hi:[0,1]
	v_pk_mul_f32 v[18:19], v[62:63], v[18:19] op_sel_hi:[0,1]
	v_pk_mul_f32 v[16:17], v[62:63], v[16:17] op_sel_hi:[0,1]
	v_pk_mul_f32 v[14:15], v[62:63], v[14:15] op_sel_hi:[0,1]
	v_pk_mul_f32 v[12:13], v[62:63], v[12:13] op_sel_hi:[0,1]
	v_pk_mul_f32 v[10:11], v[62:63], v[10:11] op_sel_hi:[0,1]
	v_pk_mul_f32 v[8:9], v[62:63], v[8:9] op_sel_hi:[0,1]
	v_pk_mul_f32 v[6:7], v[62:63], v[6:7] op_sel_hi:[0,1]
	v_pk_mul_f32 v[4:5], v[62:63], v[4:5] op_sel_hi:[0,1]
	v_pk_mul_f32 v[2:3], v[62:63], v[2:3] op_sel_hi:[0,1]
